# FFN2-down epilogue fused with the final RMSNorm (row sums by float atomics + 4-workgroup meeting per row tile); final-norm phase and its grid barrier removed
# speedup vs baseline: 1.0131x; 1.0094x over previous
.LBB0_1270:
	s_or_b64 exec, exec, s[0:1]
	s_lshl_b32 s0, s87, 9
	v_add_u32_e32 v0, s0, v230
	v_mov_b32_e32 v1, 0x10100
	v_cmp_gt_u32_e32 vcc, v1, v0
	s_and_saveexec_b64 s[2:3], vcc
	s_load_dwordx2 s[0:1], s[92:93], 0xd8
	v_lshlrev_b32_e32 v0, 2, v0
	v_mov_b32_e32 v1, 0
	s_waitcnt lgkmcnt(0)
	s_add_u32 s0, s0, 0x32a0000
	s_addc_u32 s1, s1, 0
	global_store_dword v0, v1, s[0:1]
	s_or_b64 exec, exec, s[2:3]
	s_waitcnt vmcnt(0)
	s_barrier
	s_mov_b64 s[0:1], exec
	v_readlane_b32 s2, v252, 2
	v_readlane_b32 s3, v252, 3
	s_and_b64 s[2:3], s[0:1], s[2:3]
	s_mov_b64 exec, s[2:3]
	s_cbranch_execz .LBB0_1322
	s_add_i32 s2, 0, 0x20040
	v_mov_b32_e32 v0, s2
	s_waitcnt vmcnt(0) expcnt(0) lgkmcnt(0)
	ds_read_b32 v2, v0
	s_add_i32 s2, 0, 0x20044
	v_mov_b32_e32 v0, s2
	ds_read_b32 v0, v0
	s_waitcnt lgkmcnt(1)
	v_cmp_ne_u32_e32 vcc, 0, v2
	s_cbranch_vccnz .LBB0_1286
	s_add_u32 s6, s88, 0x1000
	s_addc_u32 s7, s89, 0
	s_add_u32 s8, s88, 0x1100
	s_addc_u32 s9, s89, 0
	s_add_u32 s10, s88, 0x1200
	v_readlane_b32 s2, v252, 0
	s_addc_u32 s11, s89, 0
	s_mul_i32 s2, s91, s2
	s_add_u32 s12, s88, 0x1300
	s_mul_i32 s2, s2, s90
	s_addc_u32 s13, s89, 0
	s_mov_b32 s3, 1
	v_mov_b32_e32 v16, 0
	s_branch .LBB0_1274

.LBB0_1414:
	v_lshl_add_u32 v128, s66, 8, v218
	v_lshl_or_b32 v136, s67, 8, v220
	s_load_dwordx2 s[18:19], s[92:93], 0xc8
	s_load_dwordx2 s[20:21], s[92:93], 0xd8
	s_ashr_i32 s2, s66, 4
	v_lshlrev_b32_e32 v137, 2, v128
	v_lshlrev_b32_e32 v136, 2, v136
	s_mul_hi_i32 s31, s2, 0x9000
	s_mul_i32 s2, s2, 0x9000
	v_lshl_add_u32 v128, v128, 12, v136
	s_add_u32 s30, s50, s2
	s_addc_u32 s31, s51, s31
	v_add_u32_e32 v129, 0x10000, v128
	v_add_u32_e32 v130, 0x20000, v128
	v_add_u32_e32 v131, 0x30000, v128
	v_add_u32_e32 v132, 0x80000, v128
	v_add_u32_e32 v133, 0x90000, v128
	v_add_u32_e32 v134, 0xa0000, v128
	v_add_u32_e32 v135, 0xb0000, v128
	v_and_b32_e32 v138, 63, v230
	v_xor_b32_e32 v139, 32, v138
	v_xor_b32_e32 v138, 16, v138
	v_lshlrev_b32_e32 v139, 2, v139
	v_lshlrev_b32_e32 v138, 2, v138
	global_load_dwordx4 v[140:143], v136, s[30:31]
	global_load_dwordx4 v[144:147], v136, s[30:31] offset:64
	global_load_dwordx4 v[148:151], v136, s[30:31] offset:512
	global_load_dwordx4 v[152:155], v136, s[30:31] offset:576
	global_load_dwordx4 v[184:187], v128, s[8:9]
	global_load_dwordx4 v[188:191], v128, s[8:9] offset:64
	global_load_dwordx4 v[192:195], v128, s[8:9] offset:512
	global_load_dwordx4 v[196:199], v128, s[8:9] offset:576
	global_load_dwordx4 v[200:203], v129, s[8:9]
	global_load_dwordx4 v[204:207], v129, s[8:9] offset:64
	global_load_dwordx4 v[208:211], v129, s[8:9] offset:512
	global_load_dwordx4 v[212:215], v129, s[8:9] offset:576
	global_load_dwordx4 v[156:159], v130, s[8:9]
	global_load_dwordx4 v[160:163], v130, s[8:9] offset:64
	global_load_dwordx4 v[164:167], v130, s[8:9] offset:512
	global_load_dwordx4 v[168:171], v130, s[8:9] offset:576
	global_load_dwordx4 v[232:235], v131, s[8:9]
	global_load_dwordx4 v[236:239], v131, s[8:9] offset:64
	global_load_dwordx4 v[240:243], v131, s[8:9] offset:512
	global_load_dwordx4 v[244:247], v131, s[8:9] offset:576
	s_waitcnt lgkmcnt(0)
	s_add_u32 s20, s20, 0x32a0000
	s_addc_u32 s21, s21, 0
	s_add_u32 s22, s20, 0x40000
	s_addc_u32 s23, s21, 0
	s_waitcnt vmcnt(8)
	v_pk_mul_f32 v[140:141], v[140:141], 0.5 op_sel_hi:[1,0]
	v_pk_mul_f32 v[142:143], v[142:143], 0.5 op_sel_hi:[1,0]
	v_pk_mul_f32 v[144:145], v[144:145], 0.5 op_sel_hi:[1,0]
	v_pk_mul_f32 v[146:147], v[146:147], 0.5 op_sel_hi:[1,0]
	v_pk_mul_f32 v[148:149], v[148:149], 0.5 op_sel_hi:[1,0]
	v_pk_mul_f32 v[150:151], v[150:151], 0.5 op_sel_hi:[1,0]
	v_pk_mul_f32 v[152:153], v[152:153], 0.5 op_sel_hi:[1,0]
	v_pk_mul_f32 v[154:155], v[154:155], 0.5 op_sel_hi:[1,0]
	v_pk_fma_f32 v[124:125], v[124:125], v[140:141], v[184:185]
	v_pk_fma_f32 v[126:127], v[126:127], v[142:143], v[186:187]
	v_pk_mul_f32 v[216:217], v[124:125], v[124:125]
	v_pk_fma_f32 v[216:217], v[126:127], v[126:127], v[216:217]
	v_pk_fma_f32 v[96:97], v[96:97], v[144:145], v[188:189]
	v_pk_fma_f32 v[98:99], v[98:99], v[146:147], v[190:191]
	v_pk_fma_f32 v[216:217], v[96:97], v[96:97], v[216:217]
	v_pk_fma_f32 v[216:217], v[98:99], v[98:99], v[216:217]
	v_pk_fma_f32 v[64:65], v[64:65], v[148:149], v[192:193]
	v_pk_fma_f32 v[66:67], v[66:67], v[150:151], v[194:195]
	v_pk_fma_f32 v[216:217], v[64:65], v[64:65], v[216:217]
	v_pk_fma_f32 v[216:217], v[66:67], v[66:67], v[216:217]
	v_pk_fma_f32 v[44:45], v[44:45], v[152:153], v[196:197]
	v_pk_fma_f32 v[46:47], v[46:47], v[154:155], v[198:199]
	v_pk_fma_f32 v[216:217], v[44:45], v[44:45], v[216:217]
	v_pk_fma_f32 v[216:217], v[46:47], v[46:47], v[216:217]
	s_nop 0
	v_add_f32_e32 v224, v216, v217
	v_pk_fma_f32 v[120:121], v[120:121], v[140:141], v[200:201]
	v_pk_fma_f32 v[122:123], v[122:123], v[142:143], v[202:203]
	v_pk_mul_f32 v[216:217], v[120:121], v[120:121]
	v_pk_fma_f32 v[216:217], v[122:123], v[122:123], v[216:217]
	v_pk_fma_f32 v[88:89], v[88:89], v[144:145], v[204:205]
	v_pk_fma_f32 v[90:91], v[90:91], v[146:147], v[206:207]
	v_pk_fma_f32 v[216:217], v[88:89], v[88:89], v[216:217]
	v_pk_fma_f32 v[216:217], v[90:91], v[90:91], v[216:217]
	v_pk_fma_f32 v[56:57], v[56:57], v[148:149], v[208:209]
	v_pk_fma_f32 v[58:59], v[58:59], v[150:151], v[210:211]
	v_pk_fma_f32 v[216:217], v[56:57], v[56:57], v[216:217]
	v_pk_fma_f32 v[216:217], v[58:59], v[58:59], v[216:217]
	v_pk_fma_f32 v[36:37], v[36:37], v[152:153], v[212:213]
	v_pk_fma_f32 v[38:39], v[38:39], v[154:155], v[214:215]
	v_pk_fma_f32 v[216:217], v[36:37], v[36:37], v[216:217]
	v_pk_fma_f32 v[216:217], v[38:39], v[38:39], v[216:217]
	s_nop 0
	v_add_f32_e32 v225, v216, v217
	s_nop 1
	global_load_dwordx4 v[184:187], v132, s[8:9]
	global_load_dwordx4 v[188:191], v132, s[8:9] offset:64
	global_load_dwordx4 v[192:195], v132, s[8:9] offset:512
	global_load_dwordx4 v[196:199], v132, s[8:9] offset:576
	global_load_dwordx4 v[200:203], v133, s[8:9]
	global_load_dwordx4 v[204:207], v133, s[8:9] offset:64
	global_load_dwordx4 v[208:211], v133, s[8:9] offset:512
	global_load_dwordx4 v[212:215], v133, s[8:9] offset:576
	s_waitcnt vmcnt(8)
	v_pk_fma_f32 v[116:117], v[116:117], v[140:141], v[156:157]
	v_pk_fma_f32 v[118:119], v[118:119], v[142:143], v[158:159]
	v_pk_mul_f32 v[216:217], v[116:117], v[116:117]
	v_pk_fma_f32 v[216:217], v[118:119], v[118:119], v[216:217]
	v_pk_fma_f32 v[84:85], v[84:85], v[144:145], v[160:161]
	v_pk_fma_f32 v[86:87], v[86:87], v[146:147], v[162:163]
	v_pk_fma_f32 v[216:217], v[84:85], v[84:85], v[216:217]
	v_pk_fma_f32 v[216:217], v[86:87], v[86:87], v[216:217]
	v_pk_fma_f32 v[52:53], v[52:53], v[148:149], v[164:165]
	v_pk_fma_f32 v[54:55], v[54:55], v[150:151], v[166:167]
	v_pk_fma_f32 v[216:217], v[52:53], v[52:53], v[216:217]
	v_pk_fma_f32 v[216:217], v[54:55], v[54:55], v[216:217]
	v_pk_fma_f32 v[28:29], v[28:29], v[152:153], v[168:169]
	v_pk_fma_f32 v[30:31], v[30:31], v[154:155], v[170:171]
	v_pk_fma_f32 v[216:217], v[28:29], v[28:29], v[216:217]
	v_pk_fma_f32 v[216:217], v[30:31], v[30:31], v[216:217]
	s_nop 0
	v_add_f32_e32 v226, v216, v217
	v_pk_fma_f32 v[112:113], v[112:113], v[140:141], v[232:233]
	v_pk_fma_f32 v[114:115], v[114:115], v[142:143], v[234:235]
	v_pk_mul_f32 v[216:217], v[112:113], v[112:113]
	v_pk_fma_f32 v[216:217], v[114:115], v[114:115], v[216:217]
	v_pk_fma_f32 v[80:81], v[80:81], v[144:145], v[236:237]
	v_pk_fma_f32 v[82:83], v[82:83], v[146:147], v[238:239]
	v_pk_fma_f32 v[216:217], v[80:81], v[80:81], v[216:217]
	v_pk_fma_f32 v[216:217], v[82:83], v[82:83], v[216:217]
	v_pk_fma_f32 v[48:49], v[48:49], v[148:149], v[240:241]
	v_pk_fma_f32 v[50:51], v[50:51], v[150:151], v[242:243]
	v_pk_fma_f32 v[216:217], v[48:49], v[48:49], v[216:217]
	v_pk_fma_f32 v[216:217], v[50:51], v[50:51], v[216:217]
	v_pk_fma_f32 v[20:21], v[20:21], v[152:153], v[244:245]
	v_pk_fma_f32 v[22:23], v[22:23], v[154:155], v[246:247]
	v_pk_fma_f32 v[216:217], v[20:21], v[20:21], v[216:217]
	v_pk_fma_f32 v[216:217], v[22:23], v[22:23], v[216:217]
	s_nop 0
	v_add_f32_e32 v227, v216, v217
	s_nop 1
	global_load_dwordx4 v[156:159], v134, s[8:9]
	global_load_dwordx4 v[160:163], v134, s[8:9] offset:64
	global_load_dwordx4 v[164:167], v134, s[8:9] offset:512
	global_load_dwordx4 v[168:171], v134, s[8:9] offset:576
	global_load_dwordx4 v[232:235], v135, s[8:9]
	global_load_dwordx4 v[236:239], v135, s[8:9] offset:64
	global_load_dwordx4 v[240:243], v135, s[8:9] offset:512
	global_load_dwordx4 v[244:247], v135, s[8:9] offset:576
	s_waitcnt vmcnt(8)
	v_pk_fma_f32 v[108:109], v[108:109], v[140:141], v[184:185]
	v_pk_fma_f32 v[110:111], v[110:111], v[142:143], v[186:187]
	v_pk_mul_f32 v[216:217], v[108:109], v[108:109]
	v_pk_fma_f32 v[216:217], v[110:111], v[110:111], v[216:217]
	v_pk_fma_f32 v[76:77], v[76:77], v[144:145], v[188:189]
	v_pk_fma_f32 v[78:79], v[78:79], v[146:147], v[190:191]
	v_pk_fma_f32 v[216:217], v[76:77], v[76:77], v[216:217]
	v_pk_fma_f32 v[216:217], v[78:79], v[78:79], v[216:217]
	v_pk_fma_f32 v[40:41], v[40:41], v[148:149], v[192:193]
	v_pk_fma_f32 v[42:43], v[42:43], v[150:151], v[194:195]
	v_pk_fma_f32 v[216:217], v[40:41], v[40:41], v[216:217]
	v_pk_fma_f32 v[216:217], v[42:43], v[42:43], v[216:217]
	v_pk_fma_f32 v[12:13], v[12:13], v[152:153], v[196:197]
	v_pk_fma_f32 v[14:15], v[14:15], v[154:155], v[198:199]
	v_pk_fma_f32 v[216:217], v[12:13], v[12:13], v[216:217]
	v_pk_fma_f32 v[216:217], v[14:15], v[14:15], v[216:217]
	s_nop 0
	v_add_f32_e32 v228, v216, v217
	v_pk_fma_f32 v[104:105], v[104:105], v[140:141], v[200:201]
	v_pk_fma_f32 v[106:107], v[106:107], v[142:143], v[202:203]
	v_pk_mul_f32 v[216:217], v[104:105], v[104:105]
	v_pk_fma_f32 v[216:217], v[106:107], v[106:107], v[216:217]
	v_pk_fma_f32 v[72:73], v[72:73], v[144:145], v[204:205]
	v_pk_fma_f32 v[74:75], v[74:75], v[146:147], v[206:207]
	v_pk_fma_f32 v[216:217], v[72:73], v[72:73], v[216:217]
	v_pk_fma_f32 v[216:217], v[74:75], v[74:75], v[216:217]
	v_pk_fma_f32 v[32:33], v[32:33], v[148:149], v[208:209]
	v_pk_fma_f32 v[34:35], v[34:35], v[150:151], v[210:211]
	v_pk_fma_f32 v[216:217], v[32:33], v[32:33], v[216:217]
	v_pk_fma_f32 v[216:217], v[34:35], v[34:35], v[216:217]
	v_pk_fma_f32 v[8:9], v[8:9], v[152:153], v[212:213]
	v_pk_fma_f32 v[10:11], v[10:11], v[154:155], v[214:215]
	v_pk_fma_f32 v[216:217], v[8:9], v[8:9], v[216:217]
	v_pk_fma_f32 v[216:217], v[10:11], v[10:11], v[216:217]
	s_nop 0
	v_add_f32_e32 v229, v216, v217
	s_nop 1
	global_load_dwordx4 v[184:187], v136, s[18:19]
	global_load_dwordx4 v[188:191], v136, s[18:19] offset:64
	global_load_dwordx4 v[192:195], v136, s[18:19] offset:512
	global_load_dwordx4 v[196:199], v136, s[18:19] offset:576
	s_waitcnt vmcnt(4)
	v_pk_fma_f32 v[100:101], v[100:101], v[140:141], v[156:157]
	v_pk_fma_f32 v[102:103], v[102:103], v[142:143], v[158:159]
	v_pk_mul_f32 v[216:217], v[100:101], v[100:101]
	v_pk_fma_f32 v[216:217], v[102:103], v[102:103], v[216:217]
	v_pk_fma_f32 v[68:69], v[68:69], v[144:145], v[160:161]
	v_pk_fma_f32 v[70:71], v[70:71], v[146:147], v[162:163]
	v_pk_fma_f32 v[216:217], v[68:69], v[68:69], v[216:217]
	v_pk_fma_f32 v[216:217], v[70:71], v[70:71], v[216:217]
	v_pk_fma_f32 v[24:25], v[24:25], v[148:149], v[164:165]
	v_pk_fma_f32 v[26:27], v[26:27], v[150:151], v[166:167]
	v_pk_fma_f32 v[216:217], v[24:25], v[24:25], v[216:217]
	v_pk_fma_f32 v[216:217], v[26:27], v[26:27], v[216:217]
	v_pk_fma_f32 v[4:5], v[4:5], v[152:153], v[168:169]
	v_pk_fma_f32 v[6:7], v[6:7], v[154:155], v[170:171]
	v_pk_fma_f32 v[216:217], v[4:5], v[4:5], v[216:217]
	v_pk_fma_f32 v[216:217], v[6:7], v[6:7], v[216:217]
	s_nop 0
	v_add_f32_e32 v248, v216, v217
	v_pk_fma_f32 v[92:93], v[92:93], v[140:141], v[232:233]
	v_pk_fma_f32 v[94:95], v[94:95], v[142:143], v[234:235]
	v_pk_mul_f32 v[216:217], v[92:93], v[92:93]
	v_pk_fma_f32 v[216:217], v[94:95], v[94:95], v[216:217]
	v_pk_fma_f32 v[60:61], v[60:61], v[144:145], v[236:237]
	v_pk_fma_f32 v[62:63], v[62:63], v[146:147], v[238:239]
	v_pk_fma_f32 v[216:217], v[60:61], v[60:61], v[216:217]
	v_pk_fma_f32 v[216:217], v[62:63], v[62:63], v[216:217]
	v_pk_fma_f32 v[16:17], v[16:17], v[148:149], v[240:241]
	v_pk_fma_f32 v[18:19], v[18:19], v[150:151], v[242:243]
	v_pk_fma_f32 v[216:217], v[16:17], v[16:17], v[216:217]
	v_pk_fma_f32 v[216:217], v[18:19], v[18:19], v[216:217]
	v_pk_fma_f32 v[0:1], v[0:1], v[152:153], v[244:245]
	v_pk_fma_f32 v[2:3], v[2:3], v[154:155], v[246:247]
	v_pk_fma_f32 v[216:217], v[0:1], v[0:1], v[216:217]
	v_pk_fma_f32 v[216:217], v[2:3], v[2:3], v[216:217]
	s_nop 0
	v_add_f32_e32 v249, v216, v217
	ds_bpermute_b32 v200, v138, v224
	ds_bpermute_b32 v201, v138, v225
	ds_bpermute_b32 v202, v138, v226
	ds_bpermute_b32 v203, v138, v227
	ds_bpermute_b32 v204, v138, v228
	ds_bpermute_b32 v205, v138, v229
	ds_bpermute_b32 v206, v138, v248
	ds_bpermute_b32 v207, v138, v249
	s_waitcnt lgkmcnt(0)
	v_add_f32_e32 v224, v224, v200
	v_add_f32_e32 v225, v225, v201
	v_add_f32_e32 v226, v226, v202
	v_add_f32_e32 v227, v227, v203
	v_add_f32_e32 v228, v228, v204
	v_add_f32_e32 v229, v229, v205
	v_add_f32_e32 v248, v248, v206
	v_add_f32_e32 v249, v249, v207
	ds_bpermute_b32 v200, v139, v224
	ds_bpermute_b32 v201, v139, v225
	ds_bpermute_b32 v202, v139, v226
	ds_bpermute_b32 v203, v139, v227
	ds_bpermute_b32 v204, v139, v228
	ds_bpermute_b32 v205, v139, v229
	ds_bpermute_b32 v206, v139, v248
	ds_bpermute_b32 v207, v139, v249
	s_waitcnt lgkmcnt(0)
	v_add_f32_e32 v224, v224, v200
	v_add_f32_e32 v225, v225, v201
	v_add_f32_e32 v226, v226, v202
	v_add_f32_e32 v227, v227, v203
	v_add_f32_e32 v228, v228, v204
	v_add_f32_e32 v229, v229, v205
	v_add_f32_e32 v248, v248, v206
	v_add_f32_e32 v249, v249, v207
	s_mov_b64 exec, 0xffff
	global_atomic_add_f32 v137, v224, s[20:21]
	global_atomic_add_f32 v137, v225, s[20:21] offset:64
	global_atomic_add_f32 v137, v226, s[20:21] offset:128
	global_atomic_add_f32 v137, v227, s[20:21] offset:192
	global_atomic_add_f32 v137, v228, s[20:21] offset:512
	global_atomic_add_f32 v137, v229, s[20:21] offset:576
	global_atomic_add_f32 v137, v248, s[20:21] offset:640
	global_atomic_add_f32 v137, v249, s[20:21] offset:704
	s_mov_b64 exec, -1
	s_waitcnt vmcnt(0)
	s_barrier
	v_cmp_eq_u32_e32 vcc, 0, v230
	s_and_saveexec_b64 s[24:25], vcc
	s_cbranch_execz .Lfn_meet_p14
	s_lshl_b32 s26, s66, 2
	v_mov_b32_e32 v250, 1
	v_mov_b32_e32 v251, s26
	s_mov_b32 s27, 0
	global_atomic_add v251, v250, s[22:23]
.Lfn_spin_p14:
	global_load_dword v250, v251, s[22:23] sc1
	s_waitcnt vmcnt(0)
	v_readfirstlane_b32 s26, v250
	s_add_i32 s27, s27, 1
	s_cmp_ge_u32 s26, 4
	s_cbranch_scc1 .Lfn_meet_p14
	s_sleep 1
	s_cmp_lt_u32 s27, 0x8000
	s_cbranch_scc1 .Lfn_spin_p14
.Lfn_meet_p14:
	s_or_b64 exec, exec, s[24:25]
	s_barrier
	global_load_dword v156, v137, s[20:21] sc1
	global_load_dword v157, v137, s[20:21] offset:64 sc1
	global_load_dword v158, v137, s[20:21] offset:128 sc1
	global_load_dword v159, v137, s[20:21] offset:192 sc1
	global_load_dword v160, v137, s[20:21] offset:512 sc1
	global_load_dword v161, v137, s[20:21] offset:576 sc1
	global_load_dword v162, v137, s[20:21] offset:640 sc1
	global_load_dword v163, v137, s[20:21] offset:704 sc1
	v_mov_b32_e32 v216, 0x358637bd
	v_mov_b32_e32 v217, 0x260
	s_mov_b32 s16, 0xf800000
	s_waitcnt vmcnt(7)
	v_fmamk_f32 v156, v156, 0x3a800000, v216
	v_mul_f32_e32 v164, 0x4f800000, v156
	v_cmp_gt_f32_e32 vcc, s16, v156
	s_nop 1
	v_cndmask_b32_e32 v156, v156, v164, vcc
	v_sqrt_f32_e32 v165, v156
	s_nop 1
	v_add_u32_e32 v166, -1, v165
	v_add_u32_e32 v167, 1, v165
	v_fma_f32 v168, -v166, v165, v156
	v_fma_f32 v169, -v167, v165, v156
	v_cmp_ge_f32_e64 s[26:27], 0, v168
	s_nop 1
	v_cndmask_b32_e64 v165, v165, v166, s[26:27]
	v_cmp_lt_f32_e64 s[26:27], 0, v169
	s_nop 1
	v_cndmask_b32_e64 v165, v165, v167, s[26:27]
	v_mul_f32_e32 v166, 0x37800000, v165
	v_cndmask_b32_e32 v165, v165, v166, vcc
	v_cmp_class_f32_e32 vcc, v156, v217
	s_nop 1
	v_cndmask_b32_e32 v156, v165, v156, vcc
	v_div_scale_f32 v164, s[26:27], v156, v156, 1.0
	v_rcp_f32_e32 v165, v164
	v_div_scale_f32 v166, vcc, 1.0, v156, 1.0
	v_fma_f32 v167, -v164, v165, 1.0
	v_fmac_f32_e32 v165, v167, v165
	v_mul_f32_e32 v167, v166, v165
	v_fma_f32 v168, -v164, v167, v166
	v_fmac_f32_e32 v167, v168, v165
	v_fma_f32 v164, -v164, v167, v166
	v_div_fmas_f32 v167, v164, v165, v167
	v_div_fixup_f32 v200, v167, v156, 1.0
	s_waitcnt vmcnt(6)
	v_fmamk_f32 v157, v157, 0x3a800000, v216
	v_mul_f32_e32 v164, 0x4f800000, v157
	v_cmp_gt_f32_e32 vcc, s16, v157
	s_nop 1
	v_cndmask_b32_e32 v157, v157, v164, vcc
	v_sqrt_f32_e32 v165, v157
	s_nop 1
	v_add_u32_e32 v166, -1, v165
	v_add_u32_e32 v167, 1, v165
	v_fma_f32 v168, -v166, v165, v157
	v_fma_f32 v169, -v167, v165, v157
	v_cmp_ge_f32_e64 s[26:27], 0, v168
	s_nop 1
	v_cndmask_b32_e64 v165, v165, v166, s[26:27]
	v_cmp_lt_f32_e64 s[26:27], 0, v169
	s_nop 1
	v_cndmask_b32_e64 v165, v165, v167, s[26:27]
	v_mul_f32_e32 v166, 0x37800000, v165
	v_cndmask_b32_e32 v165, v165, v166, vcc
	v_cmp_class_f32_e32 vcc, v157, v217
	s_nop 1
	v_cndmask_b32_e32 v157, v165, v157, vcc
	v_div_scale_f32 v164, s[26:27], v157, v157, 1.0
	v_rcp_f32_e32 v165, v164
	v_div_scale_f32 v166, vcc, 1.0, v157, 1.0
	v_fma_f32 v167, -v164, v165, 1.0
	v_fmac_f32_e32 v165, v167, v165
	v_mul_f32_e32 v167, v166, v165
	v_fma_f32 v168, -v164, v167, v166
	v_fmac_f32_e32 v167, v168, v165
	v_fma_f32 v164, -v164, v167, v166
	v_div_fmas_f32 v167, v164, v165, v167
	v_div_fixup_f32 v202, v167, v157, 1.0
	s_waitcnt vmcnt(5)
	v_fmamk_f32 v158, v158, 0x3a800000, v216
	v_mul_f32_e32 v164, 0x4f800000, v158
	v_cmp_gt_f32_e32 vcc, s16, v158
	s_nop 1
	v_cndmask_b32_e32 v158, v158, v164, vcc
	v_sqrt_f32_e32 v165, v158
	s_nop 1
	v_add_u32_e32 v166, -1, v165
	v_add_u32_e32 v167, 1, v165
	v_fma_f32 v168, -v166, v165, v158
	v_fma_f32 v169, -v167, v165, v158
	v_cmp_ge_f32_e64 s[26:27], 0, v168
	s_nop 1
	v_cndmask_b32_e64 v165, v165, v166, s[26:27]
	v_cmp_lt_f32_e64 s[26:27], 0, v169
	s_nop 1
	v_cndmask_b32_e64 v165, v165, v167, s[26:27]
	v_mul_f32_e32 v166, 0x37800000, v165
	v_cndmask_b32_e32 v165, v165, v166, vcc
	v_cmp_class_f32_e32 vcc, v158, v217
	s_nop 1
	v_cndmask_b32_e32 v158, v165, v158, vcc
	v_div_scale_f32 v164, s[26:27], v158, v158, 1.0
	v_rcp_f32_e32 v165, v164
	v_div_scale_f32 v166, vcc, 1.0, v158, 1.0
	v_fma_f32 v167, -v164, v165, 1.0
	v_fmac_f32_e32 v165, v167, v165
	v_mul_f32_e32 v167, v166, v165
	v_fma_f32 v168, -v164, v167, v166
	v_fmac_f32_e32 v167, v168, v165
	v_fma_f32 v164, -v164, v167, v166
	v_div_fmas_f32 v167, v164, v165, v167
	v_div_fixup_f32 v204, v167, v158, 1.0
	s_waitcnt vmcnt(4)
	v_fmamk_f32 v159, v159, 0x3a800000, v216
	v_mul_f32_e32 v164, 0x4f800000, v159
	v_cmp_gt_f32_e32 vcc, s16, v159
	s_nop 1
	v_cndmask_b32_e32 v159, v159, v164, vcc
	v_sqrt_f32_e32 v165, v159
	s_nop 1
	v_add_u32_e32 v166, -1, v165
	v_add_u32_e32 v167, 1, v165
	v_fma_f32 v168, -v166, v165, v159
	v_fma_f32 v169, -v167, v165, v159
	v_cmp_ge_f32_e64 s[26:27], 0, v168
	s_nop 1
	v_cndmask_b32_e64 v165, v165, v166, s[26:27]
	v_cmp_lt_f32_e64 s[26:27], 0, v169
	s_nop 1
	v_cndmask_b32_e64 v165, v165, v167, s[26:27]
	v_mul_f32_e32 v166, 0x37800000, v165
	v_cndmask_b32_e32 v165, v165, v166, vcc
	v_cmp_class_f32_e32 vcc, v159, v217
	s_nop 1
	v_cndmask_b32_e32 v159, v165, v159, vcc
	v_div_scale_f32 v164, s[26:27], v159, v159, 1.0
	v_rcp_f32_e32 v165, v164
	v_div_scale_f32 v166, vcc, 1.0, v159, 1.0
	v_fma_f32 v167, -v164, v165, 1.0
	v_fmac_f32_e32 v165, v167, v165
	v_mul_f32_e32 v167, v166, v165
	v_fma_f32 v168, -v164, v167, v166
	v_fmac_f32_e32 v167, v168, v165
	v_fma_f32 v164, -v164, v167, v166
	v_div_fmas_f32 v167, v164, v165, v167
	v_div_fixup_f32 v206, v167, v159, 1.0
	s_waitcnt vmcnt(3)
	v_fmamk_f32 v160, v160, 0x3a800000, v216
	v_mul_f32_e32 v164, 0x4f800000, v160
	v_cmp_gt_f32_e32 vcc, s16, v160
	s_nop 1
	v_cndmask_b32_e32 v160, v160, v164, vcc
	v_sqrt_f32_e32 v165, v160
	s_nop 1
	v_add_u32_e32 v166, -1, v165
	v_add_u32_e32 v167, 1, v165
	v_fma_f32 v168, -v166, v165, v160
	v_fma_f32 v169, -v167, v165, v160
	v_cmp_ge_f32_e64 s[26:27], 0, v168
	s_nop 1
	v_cndmask_b32_e64 v165, v165, v166, s[26:27]
	v_cmp_lt_f32_e64 s[26:27], 0, v169
	s_nop 1
	v_cndmask_b32_e64 v165, v165, v167, s[26:27]
	v_mul_f32_e32 v166, 0x37800000, v165
	v_cndmask_b32_e32 v165, v165, v166, vcc
	v_cmp_class_f32_e32 vcc, v160, v217
	s_nop 1
	v_cndmask_b32_e32 v160, v165, v160, vcc
	v_div_scale_f32 v164, s[26:27], v160, v160, 1.0
	v_rcp_f32_e32 v165, v164
	v_div_scale_f32 v166, vcc, 1.0, v160, 1.0
	v_fma_f32 v167, -v164, v165, 1.0
	v_fmac_f32_e32 v165, v167, v165
	v_mul_f32_e32 v167, v166, v165
	v_fma_f32 v168, -v164, v167, v166
	v_fmac_f32_e32 v167, v168, v165
	v_fma_f32 v164, -v164, v167, v166
	v_div_fmas_f32 v167, v164, v165, v167
	v_div_fixup_f32 v208, v167, v160, 1.0
	s_waitcnt vmcnt(2)
	v_fmamk_f32 v161, v161, 0x3a800000, v216
	v_mul_f32_e32 v164, 0x4f800000, v161
	v_cmp_gt_f32_e32 vcc, s16, v161
	s_nop 1
	v_cndmask_b32_e32 v161, v161, v164, vcc
	v_sqrt_f32_e32 v165, v161
	s_nop 1
	v_add_u32_e32 v166, -1, v165
	v_add_u32_e32 v167, 1, v165
	v_fma_f32 v168, -v166, v165, v161
	v_fma_f32 v169, -v167, v165, v161
	v_cmp_ge_f32_e64 s[26:27], 0, v168
	s_nop 1
	v_cndmask_b32_e64 v165, v165, v166, s[26:27]
	v_cmp_lt_f32_e64 s[26:27], 0, v169
	s_nop 1
	v_cndmask_b32_e64 v165, v165, v167, s[26:27]
	v_mul_f32_e32 v166, 0x37800000, v165
	v_cndmask_b32_e32 v165, v165, v166, vcc
	v_cmp_class_f32_e32 vcc, v161, v217
	s_nop 1
	v_cndmask_b32_e32 v161, v165, v161, vcc
	v_div_scale_f32 v164, s[26:27], v161, v161, 1.0
	v_rcp_f32_e32 v165, v164
	v_div_scale_f32 v166, vcc, 1.0, v161, 1.0
	v_fma_f32 v167, -v164, v165, 1.0
	v_fmac_f32_e32 v165, v167, v165
	v_mul_f32_e32 v167, v166, v165
	v_fma_f32 v168, -v164, v167, v166
	v_fmac_f32_e32 v167, v168, v165
	v_fma_f32 v164, -v164, v167, v166
	v_div_fmas_f32 v167, v164, v165, v167
	v_div_fixup_f32 v210, v167, v161, 1.0
	s_waitcnt vmcnt(1)
	v_fmamk_f32 v162, v162, 0x3a800000, v216
	v_mul_f32_e32 v164, 0x4f800000, v162
	v_cmp_gt_f32_e32 vcc, s16, v162
	s_nop 1
	v_cndmask_b32_e32 v162, v162, v164, vcc
	v_sqrt_f32_e32 v165, v162
	s_nop 1
	v_add_u32_e32 v166, -1, v165
	v_add_u32_e32 v167, 1, v165
	v_fma_f32 v168, -v166, v165, v162
	v_fma_f32 v169, -v167, v165, v162
	v_cmp_ge_f32_e64 s[26:27], 0, v168
	s_nop 1
	v_cndmask_b32_e64 v165, v165, v166, s[26:27]
	v_cmp_lt_f32_e64 s[26:27], 0, v169
	s_nop 1
	v_cndmask_b32_e64 v165, v165, v167, s[26:27]
	v_mul_f32_e32 v166, 0x37800000, v165
	v_cndmask_b32_e32 v165, v165, v166, vcc
	v_cmp_class_f32_e32 vcc, v162, v217
	s_nop 1
	v_cndmask_b32_e32 v162, v165, v162, vcc
	v_div_scale_f32 v164, s[26:27], v162, v162, 1.0
	v_rcp_f32_e32 v165, v164
	v_div_scale_f32 v166, vcc, 1.0, v162, 1.0
	v_fma_f32 v167, -v164, v165, 1.0
	v_fmac_f32_e32 v165, v167, v165
	v_mul_f32_e32 v167, v166, v165
	v_fma_f32 v168, -v164, v167, v166
	v_fmac_f32_e32 v167, v168, v165
	v_fma_f32 v164, -v164, v167, v166
	v_div_fmas_f32 v167, v164, v165, v167
	v_div_fixup_f32 v212, v167, v162, 1.0
	s_waitcnt vmcnt(0)
	v_fmamk_f32 v163, v163, 0x3a800000, v216
	v_mul_f32_e32 v164, 0x4f800000, v163
	v_cmp_gt_f32_e32 vcc, s16, v163
	s_nop 1
	v_cndmask_b32_e32 v163, v163, v164, vcc
	v_sqrt_f32_e32 v165, v163
	s_nop 1
	v_add_u32_e32 v166, -1, v165
	v_add_u32_e32 v167, 1, v165
	v_fma_f32 v168, -v166, v165, v163
	v_fma_f32 v169, -v167, v165, v163
	v_cmp_ge_f32_e64 s[26:27], 0, v168
	s_nop 1
	v_cndmask_b32_e64 v165, v165, v166, s[26:27]
	v_cmp_lt_f32_e64 s[26:27], 0, v169
	s_nop 1
	v_cndmask_b32_e64 v165, v165, v167, s[26:27]
	v_mul_f32_e32 v166, 0x37800000, v165
	v_cndmask_b32_e32 v165, v165, v166, vcc
	v_cmp_class_f32_e32 vcc, v163, v217
	s_nop 1
	v_cndmask_b32_e32 v163, v165, v163, vcc
	v_div_scale_f32 v164, s[26:27], v163, v163, 1.0
	v_rcp_f32_e32 v165, v164
	v_div_scale_f32 v166, vcc, 1.0, v163, 1.0
	v_fma_f32 v167, -v164, v165, 1.0
	v_fmac_f32_e32 v165, v167, v165
	v_mul_f32_e32 v167, v166, v165
	v_fma_f32 v168, -v164, v167, v166
	v_fmac_f32_e32 v167, v168, v165
	v_fma_f32 v164, -v164, v167, v166
	v_div_fmas_f32 v167, v164, v165, v167
	v_div_fixup_f32 v214, v167, v163, 1.0
	v_pk_mul_f32 v[124:125], v[124:125], v[200:201] op_sel_hi:[1,0]
	v_pk_mul_f32 v[126:127], v[126:127], v[200:201] op_sel_hi:[1,0]
	v_pk_mul_f32 v[124:125], v[184:185], v[124:125]
	v_pk_mul_f32 v[126:127], v[186:187], v[126:127]
	v_pk_mul_f32 v[96:97], v[96:97], v[200:201] op_sel_hi:[1,0]
	v_pk_mul_f32 v[98:99], v[98:99], v[200:201] op_sel_hi:[1,0]
	v_pk_mul_f32 v[96:97], v[188:189], v[96:97]
	v_pk_mul_f32 v[98:99], v[190:191], v[98:99]
	v_pk_mul_f32 v[64:65], v[64:65], v[200:201] op_sel_hi:[1,0]
	v_pk_mul_f32 v[66:67], v[66:67], v[200:201] op_sel_hi:[1,0]
	v_pk_mul_f32 v[64:65], v[192:193], v[64:65]
	v_pk_mul_f32 v[66:67], v[194:195], v[66:67]
	v_pk_mul_f32 v[44:45], v[44:45], v[200:201] op_sel_hi:[1,0]
	v_pk_mul_f32 v[46:47], v[46:47], v[200:201] op_sel_hi:[1,0]
	v_pk_mul_f32 v[44:45], v[196:197], v[44:45]
	v_pk_mul_f32 v[46:47], v[198:199], v[46:47]
	global_store_dwordx4 v128, v[124:127], s[8:9]
	global_store_dwordx4 v128, v[96:99], s[8:9] offset:64
	global_store_dwordx4 v128, v[64:67], s[8:9] offset:512
	global_store_dwordx4 v128, v[44:47], s[8:9] offset:576
	v_pk_mul_f32 v[120:121], v[120:121], v[202:203] op_sel_hi:[1,0]
	v_pk_mul_f32 v[122:123], v[122:123], v[202:203] op_sel_hi:[1,0]
	v_pk_mul_f32 v[120:121], v[184:185], v[120:121]
	v_pk_mul_f32 v[122:123], v[186:187], v[122:123]
	v_pk_mul_f32 v[88:89], v[88:89], v[202:203] op_sel_hi:[1,0]
	v_pk_mul_f32 v[90:91], v[90:91], v[202:203] op_sel_hi:[1,0]
	v_pk_mul_f32 v[88:89], v[188:189], v[88:89]
	v_pk_mul_f32 v[90:91], v[190:191], v[90:91]
	v_pk_mul_f32 v[56:57], v[56:57], v[202:203] op_sel_hi:[1,0]
	v_pk_mul_f32 v[58:59], v[58:59], v[202:203] op_sel_hi:[1,0]
	v_pk_mul_f32 v[56:57], v[192:193], v[56:57]
	v_pk_mul_f32 v[58:59], v[194:195], v[58:59]
	v_pk_mul_f32 v[36:37], v[36:37], v[202:203] op_sel_hi:[1,0]
	v_pk_mul_f32 v[38:39], v[38:39], v[202:203] op_sel_hi:[1,0]
	v_pk_mul_f32 v[36:37], v[196:197], v[36:37]
	v_pk_mul_f32 v[38:39], v[198:199], v[38:39]
	global_store_dwordx4 v129, v[120:123], s[8:9]
	global_store_dwordx4 v129, v[88:91], s[8:9] offset:64
	global_store_dwordx4 v129, v[56:59], s[8:9] offset:512
	global_store_dwordx4 v129, v[36:39], s[8:9] offset:576
	v_pk_mul_f32 v[116:117], v[116:117], v[204:205] op_sel_hi:[1,0]
	v_pk_mul_f32 v[118:119], v[118:119], v[204:205] op_sel_hi:[1,0]
	v_pk_mul_f32 v[116:117], v[184:185], v[116:117]
	v_pk_mul_f32 v[118:119], v[186:187], v[118:119]
	v_pk_mul_f32 v[84:85], v[84:85], v[204:205] op_sel_hi:[1,0]
	v_pk_mul_f32 v[86:87], v[86:87], v[204:205] op_sel_hi:[1,0]
	v_pk_mul_f32 v[84:85], v[188:189], v[84:85]
	v_pk_mul_f32 v[86:87], v[190:191], v[86:87]
	v_pk_mul_f32 v[52:53], v[52:53], v[204:205] op_sel_hi:[1,0]
	v_pk_mul_f32 v[54:55], v[54:55], v[204:205] op_sel_hi:[1,0]
	v_pk_mul_f32 v[52:53], v[192:193], v[52:53]
	v_pk_mul_f32 v[54:55], v[194:195], v[54:55]
	v_pk_mul_f32 v[28:29], v[28:29], v[204:205] op_sel_hi:[1,0]
	v_pk_mul_f32 v[30:31], v[30:31], v[204:205] op_sel_hi:[1,0]
	v_pk_mul_f32 v[28:29], v[196:197], v[28:29]
	v_pk_mul_f32 v[30:31], v[198:199], v[30:31]
	global_store_dwordx4 v130, v[116:119], s[8:9]
	global_store_dwordx4 v130, v[84:87], s[8:9] offset:64
	global_store_dwordx4 v130, v[52:55], s[8:9] offset:512
	global_store_dwordx4 v130, v[28:31], s[8:9] offset:576
	v_pk_mul_f32 v[112:113], v[112:113], v[206:207] op_sel_hi:[1,0]
	v_pk_mul_f32 v[114:115], v[114:115], v[206:207] op_sel_hi:[1,0]
	v_pk_mul_f32 v[112:113], v[184:185], v[112:113]
	v_pk_mul_f32 v[114:115], v[186:187], v[114:115]
	v_pk_mul_f32 v[80:81], v[80:81], v[206:207] op_sel_hi:[1,0]
	v_pk_mul_f32 v[82:83], v[82:83], v[206:207] op_sel_hi:[1,0]
	v_pk_mul_f32 v[80:81], v[188:189], v[80:81]
	v_pk_mul_f32 v[82:83], v[190:191], v[82:83]
	v_pk_mul_f32 v[48:49], v[48:49], v[206:207] op_sel_hi:[1,0]
	v_pk_mul_f32 v[50:51], v[50:51], v[206:207] op_sel_hi:[1,0]
	v_pk_mul_f32 v[48:49], v[192:193], v[48:49]
	v_pk_mul_f32 v[50:51], v[194:195], v[50:51]
	v_pk_mul_f32 v[20:21], v[20:21], v[206:207] op_sel_hi:[1,0]
	v_pk_mul_f32 v[22:23], v[22:23], v[206:207] op_sel_hi:[1,0]
	v_pk_mul_f32 v[20:21], v[196:197], v[20:21]
	v_pk_mul_f32 v[22:23], v[198:199], v[22:23]
	global_store_dwordx4 v131, v[112:115], s[8:9]
	global_store_dwordx4 v131, v[80:83], s[8:9] offset:64
	global_store_dwordx4 v131, v[48:51], s[8:9] offset:512
	global_store_dwordx4 v131, v[20:23], s[8:9] offset:576
	v_pk_mul_f32 v[108:109], v[108:109], v[208:209] op_sel_hi:[1,0]
	v_pk_mul_f32 v[110:111], v[110:111], v[208:209] op_sel_hi:[1,0]
	v_pk_mul_f32 v[108:109], v[184:185], v[108:109]
	v_pk_mul_f32 v[110:111], v[186:187], v[110:111]
	v_pk_mul_f32 v[76:77], v[76:77], v[208:209] op_sel_hi:[1,0]
	v_pk_mul_f32 v[78:79], v[78:79], v[208:209] op_sel_hi:[1,0]
	v_pk_mul_f32 v[76:77], v[188:189], v[76:77]
	v_pk_mul_f32 v[78:79], v[190:191], v[78:79]
	v_pk_mul_f32 v[40:41], v[40:41], v[208:209] op_sel_hi:[1,0]
	v_pk_mul_f32 v[42:43], v[42:43], v[208:209] op_sel_hi:[1,0]
	v_pk_mul_f32 v[40:41], v[192:193], v[40:41]
	v_pk_mul_f32 v[42:43], v[194:195], v[42:43]
	v_pk_mul_f32 v[12:13], v[12:13], v[208:209] op_sel_hi:[1,0]
	v_pk_mul_f32 v[14:15], v[14:15], v[208:209] op_sel_hi:[1,0]
	v_pk_mul_f32 v[12:13], v[196:197], v[12:13]
	v_pk_mul_f32 v[14:15], v[198:199], v[14:15]
	global_store_dwordx4 v132, v[108:111], s[8:9]
	global_store_dwordx4 v132, v[76:79], s[8:9] offset:64
	global_store_dwordx4 v132, v[40:43], s[8:9] offset:512
	global_store_dwordx4 v132, v[12:15], s[8:9] offset:576
	v_pk_mul_f32 v[104:105], v[104:105], v[210:211] op_sel_hi:[1,0]
	v_pk_mul_f32 v[106:107], v[106:107], v[210:211] op_sel_hi:[1,0]
	v_pk_mul_f32 v[104:105], v[184:185], v[104:105]
	v_pk_mul_f32 v[106:107], v[186:187], v[106:107]
	v_pk_mul_f32 v[72:73], v[72:73], v[210:211] op_sel_hi:[1,0]
	v_pk_mul_f32 v[74:75], v[74:75], v[210:211] op_sel_hi:[1,0]
	v_pk_mul_f32 v[72:73], v[188:189], v[72:73]
	v_pk_mul_f32 v[74:75], v[190:191], v[74:75]
	v_pk_mul_f32 v[32:33], v[32:33], v[210:211] op_sel_hi:[1,0]
	v_pk_mul_f32 v[34:35], v[34:35], v[210:211] op_sel_hi:[1,0]
	v_pk_mul_f32 v[32:33], v[192:193], v[32:33]
	v_pk_mul_f32 v[34:35], v[194:195], v[34:35]
	v_pk_mul_f32 v[8:9], v[8:9], v[210:211] op_sel_hi:[1,0]
	v_pk_mul_f32 v[10:11], v[10:11], v[210:211] op_sel_hi:[1,0]
	v_pk_mul_f32 v[8:9], v[196:197], v[8:9]
	v_pk_mul_f32 v[10:11], v[198:199], v[10:11]
	global_store_dwordx4 v133, v[104:107], s[8:9]
	global_store_dwordx4 v133, v[72:75], s[8:9] offset:64
	global_store_dwordx4 v133, v[32:35], s[8:9] offset:512
	global_store_dwordx4 v133, v[8:11], s[8:9] offset:576
	v_pk_mul_f32 v[100:101], v[100:101], v[212:213] op_sel_hi:[1,0]
	v_pk_mul_f32 v[102:103], v[102:103], v[212:213] op_sel_hi:[1,0]
	v_pk_mul_f32 v[100:101], v[184:185], v[100:101]
	v_pk_mul_f32 v[102:103], v[186:187], v[102:103]
	v_pk_mul_f32 v[68:69], v[68:69], v[212:213] op_sel_hi:[1,0]
	v_pk_mul_f32 v[70:71], v[70:71], v[212:213] op_sel_hi:[1,0]
	v_pk_mul_f32 v[68:69], v[188:189], v[68:69]
	v_pk_mul_f32 v[70:71], v[190:191], v[70:71]
	v_pk_mul_f32 v[24:25], v[24:25], v[212:213] op_sel_hi:[1,0]
	v_pk_mul_f32 v[26:27], v[26:27], v[212:213] op_sel_hi:[1,0]
	v_pk_mul_f32 v[24:25], v[192:193], v[24:25]
	v_pk_mul_f32 v[26:27], v[194:195], v[26:27]
	v_pk_mul_f32 v[4:5], v[4:5], v[212:213] op_sel_hi:[1,0]
	v_pk_mul_f32 v[6:7], v[6:7], v[212:213] op_sel_hi:[1,0]
	v_pk_mul_f32 v[4:5], v[196:197], v[4:5]
	v_pk_mul_f32 v[6:7], v[198:199], v[6:7]
	global_store_dwordx4 v134, v[100:103], s[8:9]
	global_store_dwordx4 v134, v[68:71], s[8:9] offset:64
	global_store_dwordx4 v134, v[24:27], s[8:9] offset:512
	global_store_dwordx4 v134, v[4:7], s[8:9] offset:576
	v_pk_mul_f32 v[92:93], v[92:93], v[214:215] op_sel_hi:[1,0]
	v_pk_mul_f32 v[94:95], v[94:95], v[214:215] op_sel_hi:[1,0]
	v_pk_mul_f32 v[92:93], v[184:185], v[92:93]
	v_pk_mul_f32 v[94:95], v[186:187], v[94:95]
	v_pk_mul_f32 v[60:61], v[60:61], v[214:215] op_sel_hi:[1,0]
	v_pk_mul_f32 v[62:63], v[62:63], v[214:215] op_sel_hi:[1,0]
	v_pk_mul_f32 v[60:61], v[188:189], v[60:61]
	v_pk_mul_f32 v[62:63], v[190:191], v[62:63]
	v_pk_mul_f32 v[16:17], v[16:17], v[214:215] op_sel_hi:[1,0]
	v_pk_mul_f32 v[18:19], v[18:19], v[214:215] op_sel_hi:[1,0]
	v_pk_mul_f32 v[16:17], v[192:193], v[16:17]
	v_pk_mul_f32 v[18:19], v[194:195], v[18:19]
	v_pk_mul_f32 v[0:1], v[0:1], v[214:215] op_sel_hi:[1,0]
	v_pk_mul_f32 v[2:3], v[2:3], v[214:215] op_sel_hi:[1,0]
	v_pk_mul_f32 v[0:1], v[196:197], v[0:1]
	v_pk_mul_f32 v[2:3], v[198:199], v[2:3]
	global_store_dwordx4 v135, v[92:95], s[8:9]
	global_store_dwordx4 v135, v[60:63], s[8:9] offset:64
	global_store_dwordx4 v135, v[16:19], s[8:9] offset:512
	global_store_dwordx4 v135, v[0:3], s[8:9] offset:576
	s_mov_b64 s[30:31], -1
	s_and_b64 vcc, exec, s[4:5]
	s_cbranch_vccnz .LBB0_1399
	s_andn2_b64 vcc, exec, s[12:13]
	s_cbranch_vccnz .LBB0_1398
	s_barrier
	s_branch .LBB0_1398

.LBB0_1418:
	s_waitcnt vmcnt(0)
	s_endpgm
